# NSA lean schedule: MFMAs placed earlier (gap 5)
# speedup vs baseline: 1.0056x; 1.0056x over previous
.LBB0_1463:
	s_cmp_eq_u32 s63, 2
	s_cbranch_scc0 .Lm2_no
	s_add_i32 s98, s54, 1
	s_cmp_ge_i32 s98, s53
	s_cbranch_scc1 .Lm2_no
	v_cmp_eq_f32_e64 s[18:19], s73, v222
	s_cmp_lg_u64 s[18:19], 0
	s_cbranch_scc1 .Lm2_no
	s_add_i32 s21, s38, s45
	s_and_b32 s20, s45, 2
	s_add_i32 s54, s54, 1
	s_mov_b64 s[94:95], 0
	s_lshl_b32 s30, s20, 13
	v_add_u32_e32 v8, s30, v169
	v_add_u32_e32 v3, s30, v193
	s_lshr_b32 s0, s21, 5
	s_cmp_lt_u32 s0, 2
	s_cselect_b64 s[98:99], -1, 0
	s_bitcmp1_b32 s0, 0
	s_cselect_b64 s[0:1], -1, 0
	s_and_b32 s28, s21, 31
	v_cndmask_b32_e64 v5, v130, v131, s[0:1]
	v_cndmask_b32_e64 v6, v132, v133, s[0:1]
	v_cndmask_b32_e64 v5, v6, v5, s[98:99]
	v_lshrrev_b32_e32 v5, s28, v5
	v_and_b32_e32 v6, 1, v5
	v_bfe_u32 v9, v5, 1, 1
	v_xor_b32_e32 v7, 0x80000000, v222
	v_cmp_eq_u32_e32 vcc, 1, v6
	v_cmp_eq_u32_e64 s[98:99], 1, v9
	v_add_f32_e32 v4, v7, v201
	s_cmp_lg_u64 vcc, 0
	s_cselect_b32 s55, 1, 0
	v_cndmask_b32_e32 v82, v4, v7, vcc
	v_cndmask_b32_e64 v50, v4, v7, s[98:99]
	s_cmp_lg_u64 s[98:99], 0
	s_cselect_b32 s0, 2, 0
	s_or_b32 s55, s55, s0
	s_cmp_eq_u32 s55, 3
	s_cbranch_scc0 .Lm2_partial
	ds_read_b128 v[10:13], v8
	ds_read_b128 v[14:17], v8 offset:512
	ds_read_b128 v[174:177], v8 offset:2048
	ds_read_b128 v[178:181], v8 offset:2560
	ds_read_b128 v[182:185], v8 offset:4096
	ds_read_b128 v[186:189], v8 offset:4608
	ds_read_b128 v[228:231], v8 offset:6144
	ds_read_b128 v[232:235], v8 offset:6656
	v_mov_b32_e32 v83, v82
	v_mov_b64_e32 v[84:85], v[82:83]
	v_mov_b64_e32 v[86:87], v[82:83]
	v_mov_b64_e32 v[88:89], v[82:83]
	v_mov_b64_e32 v[90:91], v[82:83]
	v_mov_b64_e32 v[92:93], v[82:83]
	v_mov_b64_e32 v[94:95], v[82:83]
	v_mov_b64_e32 v[96:97], v[82:83]
	v_mov_b32_e32 v51, v50
	v_mov_b64_e32 v[52:53], v[50:51]
	s_waitcnt lgkmcnt(7)
	v_mfma_f32_32x32x16_bf16 v[98:113], v[10:13], v[114:117], v[82:97]
	ds_read_b128 v[10:13], v8 offset:8192
	v_mov_b64_e32 v[54:55], v[50:51]
	v_mov_b64_e32 v[56:57], v[50:51]
	v_mov_b64_e32 v[58:59], v[50:51]
	v_mov_b64_e32 v[60:61], v[50:51]
	v_mov_b64_e32 v[62:63], v[50:51]
	s_waitcnt lgkmcnt(7)
	v_mfma_f32_32x32x16_bf16 v[82:97], v[14:17], v[114:117], v[82:97]
	ds_read_b128 v[14:17], v8 offset:8704
	v_mov_b64_e32 v[64:65], v[50:51]
	s_add_i32 s0, s21, 2
	s_ashr_i32 s1, s0, 31
	s_lshl_b64 s[0:1], s[0:1], 6
	s_add_u32 s0, s0, s84
	s_waitcnt lgkmcnt(7)
	v_mfma_f32_32x32x16_bf16 v[98:113], v[174:177], v[118:121], v[98:113]
	ds_read_b128 v[174:177], v8 offset:10240
	s_addc_u32 s1, s1, s85
	s_lshl_b64 s[0:1], s[0:1], 7
	s_add_u32 s28, s86, s0
	s_addc_u32 s29, s87, s1
	s_sub_i32 s31, s37, s30
	s_waitcnt lgkmcnt(7)
	v_mfma_f32_32x32x16_bf16 v[82:97], v[178:181], v[118:121], v[82:97]
	ds_read_b128 v[178:181], v8 offset:10752
	s_add_i32 s31, s31, 0x4000
	v_lshlrev_b32_e32 v5, 7, v138
	s_mov_b32 m0, s31
	s_movk_i32 s30, 0x80
	global_load_lds_dwordx4 v5, s[28:29]
	s_waitcnt lgkmcnt(7)
	v_mfma_f32_32x32x16_bf16 v[98:113], v[182:185], v[122:125], v[98:113]
	ds_read_b128 v[182:185], v8 offset:12288
	v_mad_u64_u32 v[226:227], vcc, v168, s30, v[134:135]
	s_add_i32 s31, s31, 0x8000
	v_lshl_add_u64 v[6:7], v[226:227], 0, s[0:1]
	s_mov_b32 m0, s31
	s_cmp_lt_i32 s45, s44
	s_waitcnt lgkmcnt(7)
	v_mfma_f32_32x32x16_bf16 v[82:97], v[186:189], v[122:125], v[82:97]
	ds_read_b128 v[186:189], v8 offset:12800
	global_load_lds_dwordx4 v[6:7], off
	s_cselect_b32 s98, 0x2000, 0
	s_add_u32 s28, s28, s98
	s_waitcnt lgkmcnt(7)
	v_mfma_f32_32x32x16_bf16 v[98:113], v[228:231], v[126:129], v[98:113]
	ds_read_b128 v[228:231], v8 offset:14336
	s_addc_u32 s29, s29, 0
	s_add_u32 s0, s0, s98
	s_addc_u32 s1, s1, 0
	s_sub_i32 s31, s31, 0x6000
	s_mov_b32 m0, s31
	s_waitcnt lgkmcnt(7)
	v_mfma_f32_32x32x16_bf16 v[82:97], v[232:235], v[126:129], v[82:97]
	ds_read_b128 v[232:235], v8 offset:14848
	v_lshl_add_u64 v[6:7], v[226:227], 0, s[0:1]
	global_load_lds_dwordx4 v5, s[28:29]
	s_add_i32 s31, s31, 0x8000
	s_waitcnt lgkmcnt(7)
	v_mfma_f32_32x32x16_bf16 v[66:81], v[10:13], v[114:117], v[50:65]
	ds_read_b64_tr_b16 v[10:11], v3 offset:32768
	ds_read_b64_tr_b16 v[12:13], v3 offset:33280
	s_mov_b32 m0, s31
	s_nop 0
	global_load_lds_dwordx4 v[6:7], off
	s_waitcnt lgkmcnt(8)
	v_mfma_f32_32x32x16_bf16 v[50:65], v[14:17], v[114:117], v[50:65]
	ds_read_b64_tr_b16 v[14:15], v3 offset:36864
	ds_read_b64_tr_b16 v[16:17], v3 offset:37376
	v_exp_f32_e32 v98, v98
	v_exp_f32_e32 v99, v99
	v_exp_f32_e32 v100, v100
	s_waitcnt lgkmcnt(9)
	v_mfma_f32_32x32x16_bf16 v[66:81], v[174:177], v[118:121], v[66:81]
	ds_read_b64_tr_b16 v[174:175], v3 offset:33792
	ds_read_b64_tr_b16 v[176:177], v3 offset:34304
	v_exp_f32_e32 v101, v101
	v_exp_f32_e32 v102, v102
	v_exp_f32_e32 v103, v103
	s_waitcnt lgkmcnt(10)
	v_mfma_f32_32x32x16_bf16 v[50:65], v[178:181], v[118:121], v[50:65]
	ds_read_b64_tr_b16 v[178:179], v3 offset:37888
	ds_read_b64_tr_b16 v[180:181], v3 offset:38400
	v_exp_f32_e32 v104, v104
	v_exp_f32_e32 v105, v105
	v_cvt_pk_bf16_f32 v236, v98, v99
	s_waitcnt lgkmcnt(11)
	v_mfma_f32_32x32x16_bf16 v[66:81], v[182:185], v[122:125], v[66:81]
	ds_read_b64_tr_b16 v[182:183], v3 offset:34816
	ds_read_b64_tr_b16 v[184:185], v3 offset:35328
	v_cvt_pk_bf16_f32 v237, v100, v101
	v_cvt_pk_bf16_f32 v238, v102, v103
	v_cvt_pk_bf16_f32 v239, v104, v105
	v_exp_f32_e32 v106, v106
	s_waitcnt lgkmcnt(12)
	v_mfma_f32_32x32x16_bf16 v[50:65], v[186:189], v[122:125], v[50:65]
	ds_read_b64_tr_b16 v[186:187], v3 offset:38912
	ds_read_b64_tr_b16 v[188:189], v3 offset:39424
	v_exp_f32_e32 v107, v107
	v_exp_f32_e32 v108, v108
	v_exp_f32_e32 v109, v109
	s_waitcnt lgkmcnt(13)
	v_mfma_f32_32x32x16_bf16 v[66:81], v[228:231], v[126:129], v[66:81]
	ds_read_b64_tr_b16 v[228:229], v3 offset:35840
	ds_read_b64_tr_b16 v[230:231], v3 offset:36352
	v_exp_f32_e32 v110, v110
	v_exp_f32_e32 v111, v111
	v_exp_f32_e32 v112, v112
	s_waitcnt lgkmcnt(14)
	v_mfma_f32_32x32x16_bf16 v[50:65], v[232:235], v[126:129], v[50:65]
	s_waitcnt lgkmcnt(13)
	ds_read_b64_tr_b16 v[232:233], v3 offset:39936
	ds_read_b64_tr_b16 v[234:235], v3 offset:40448
	v_exp_f32_e32 v113, v113
	v_cvt_pk_bf16_f32 v240, v106, v107
	v_cvt_pk_bf16_f32 v241, v108, v109
	v_cvt_pk_bf16_f32 v242, v110, v111
	s_waitcnt lgkmcnt(14)
	v_mfma_f32_32x32x16_bf16 v[34:49], v[236:239], v[10:13], v[34:49]
	s_waitcnt lgkmcnt(13)
	ds_read_b64_tr_b16 v[10:11], v3 offset:40960
	ds_read_b64_tr_b16 v[12:13], v3 offset:41472
	v_cvt_pk_bf16_f32 v243, v112, v113
	v_exp_f32_e32 v82, v82
	v_exp_f32_e32 v83, v83
	s_waitcnt lgkmcnt(14)
	v_mfma_f32_32x32x16_bf16 v[18:33], v[236:239], v[14:17], v[18:33]
	s_waitcnt lgkmcnt(13)
	ds_read_b64_tr_b16 v[14:15], v3 offset:45056
	ds_read_b64_tr_b16 v[16:17], v3 offset:45568
	v_exp_f32_e32 v84, v84
	v_exp_f32_e32 v85, v85
	v_exp_f32_e32 v86, v86
	s_waitcnt lgkmcnt(14)
	v_mfma_f32_32x32x16_bf16 v[34:49], v[240:243], v[174:177], v[34:49]
	s_waitcnt lgkmcnt(13)
	ds_read_b64_tr_b16 v[174:175], v3 offset:41984
	ds_read_b64_tr_b16 v[176:177], v3 offset:42496
	v_exp_f32_e32 v87, v87
	v_exp_f32_e32 v88, v88
	v_exp_f32_e32 v89, v89
	s_waitcnt lgkmcnt(14)
	v_mfma_f32_32x32x16_bf16 v[18:33], v[240:243], v[178:181], v[18:33]
	s_waitcnt lgkmcnt(13)
	ds_read_b64_tr_b16 v[178:179], v3 offset:46080
	ds_read_b64_tr_b16 v[180:181], v3 offset:46592
	v_cvt_pk_bf16_f32 v244, v82, v83
	v_cvt_pk_bf16_f32 v245, v84, v85
	v_cvt_pk_bf16_f32 v246, v86, v87
	v_cvt_pk_bf16_f32 v247, v88, v89
	v_exp_f32_e32 v90, v90
	v_exp_f32_e32 v91, v91
	s_waitcnt lgkmcnt(14)
	v_mfma_f32_32x32x16_bf16 v[34:49], v[244:247], v[182:185], v[34:49]
	s_waitcnt lgkmcnt(13)
	ds_read_b64_tr_b16 v[182:183], v3 offset:43008
	ds_read_b64_tr_b16 v[184:185], v3 offset:43520
	v_exp_f32_e32 v92, v92
	v_exp_f32_e32 v93, v93
	v_exp_f32_e32 v94, v94
	s_waitcnt lgkmcnt(14)
	v_mfma_f32_32x32x16_bf16 v[18:33], v[244:247], v[186:189], v[18:33]
	s_waitcnt lgkmcnt(13)
	ds_read_b64_tr_b16 v[186:187], v3 offset:47104
	ds_read_b64_tr_b16 v[188:189], v3 offset:47616
	v_exp_f32_e32 v95, v95
	v_exp_f32_e32 v96, v96
	v_exp_f32_e32 v97, v97
	v_cvt_pk_bf16_f32 v248, v90, v91
	v_cvt_pk_bf16_f32 v249, v92, v93
	v_cvt_pk_bf16_f32 v250, v94, v95
	v_cvt_pk_bf16_f32 v251, v96, v97
	v_exp_f32_e32 v66, v66
	v_exp_f32_e32 v67, v67
	s_waitcnt lgkmcnt(14)
	v_mfma_f32_32x32x16_bf16 v[34:49], v[248:251], v[228:231], v[34:49]
	s_waitcnt lgkmcnt(13)
	ds_read_b64_tr_b16 v[228:229], v3 offset:44032
	ds_read_b64_tr_b16 v[230:231], v3 offset:44544
	v_exp_f32_e32 v68, v68
	v_exp_f32_e32 v69, v69
	v_exp_f32_e32 v70, v70
	s_waitcnt lgkmcnt(14)
	v_mfma_f32_32x32x16_bf16 v[18:33], v[248:251], v[232:235], v[18:33]
	s_waitcnt lgkmcnt(13)
	ds_read_b64_tr_b16 v[232:233], v3 offset:48128
	ds_read_b64_tr_b16 v[234:235], v3 offset:48640
	v_exp_f32_e32 v71, v71
	v_exp_f32_e32 v72, v72
	v_exp_f32_e32 v73, v73
	v_cvt_pk_bf16_f32 v236, v66, v67
	v_cvt_pk_bf16_f32 v237, v68, v69
	v_cvt_pk_bf16_f32 v238, v70, v71
	v_cvt_pk_bf16_f32 v239, v72, v73
	v_exp_f32_e32 v74, v74
	v_exp_f32_e32 v75, v75
	s_waitcnt lgkmcnt(14)
	v_mfma_f32_32x32x16_bf16 v[34:49], v[236:239], v[10:13], v[34:49]
	v_exp_f32_e32 v76, v76
	v_exp_f32_e32 v77, v77
	v_exp_f32_e32 v78, v78
	s_waitcnt lgkmcnt(12)
	v_mfma_f32_32x32x16_bf16 v[18:33], v[236:239], v[14:17], v[18:33]
	v_exp_f32_e32 v79, v79
	v_exp_f32_e32 v80, v80
	v_exp_f32_e32 v81, v81
	v_cvt_pk_bf16_f32 v240, v74, v75
	v_cvt_pk_bf16_f32 v241, v76, v77
	v_cvt_pk_bf16_f32 v242, v78, v79
	v_cvt_pk_bf16_f32 v243, v80, v81
	v_exp_f32_e32 v50, v50
	v_exp_f32_e32 v51, v51
	s_waitcnt lgkmcnt(10)
	v_mfma_f32_32x32x16_bf16 v[34:49], v[240:243], v[174:177], v[34:49]
	v_exp_f32_e32 v52, v52
	v_exp_f32_e32 v53, v53
	v_exp_f32_e32 v54, v54
	s_waitcnt lgkmcnt(8)
	v_mfma_f32_32x32x16_bf16 v[18:33], v[240:243], v[178:181], v[18:33]
	v_exp_f32_e32 v55, v55
	v_exp_f32_e32 v56, v56
	v_exp_f32_e32 v57, v57
	v_cvt_pk_bf16_f32 v244, v50, v51
	v_cvt_pk_bf16_f32 v245, v52, v53
	v_cvt_pk_bf16_f32 v246, v54, v55
	v_cvt_pk_bf16_f32 v247, v56, v57
	v_exp_f32_e32 v58, v58
	v_exp_f32_e32 v59, v59
	s_waitcnt lgkmcnt(6)
	v_mfma_f32_32x32x16_bf16 v[34:49], v[244:247], v[182:185], v[34:49]
	v_exp_f32_e32 v60, v60
	v_exp_f32_e32 v61, v61
	v_exp_f32_e32 v62, v62
	s_waitcnt lgkmcnt(4)
	v_mfma_f32_32x32x16_bf16 v[18:33], v[244:247], v[186:189], v[18:33]
	v_exp_f32_e32 v63, v63
	v_exp_f32_e32 v64, v64
	v_exp_f32_e32 v65, v65
	v_cvt_pk_bf16_f32 v248, v58, v59
	v_cvt_pk_bf16_f32 v249, v60, v61
	v_cvt_pk_bf16_f32 v250, v62, v63
	v_cvt_pk_bf16_f32 v251, v64, v65
	v_pk_add_f32 v[4:5], v[98:99], v[100:101]
	v_pk_add_f32 v[6:7], v[82:83], v[84:85]
	s_waitcnt lgkmcnt(2)
	v_mfma_f32_32x32x16_bf16 v[34:49], v[248:251], v[228:231], v[34:49]
	v_pk_add_f32 v[4:5], v[4:5], v[102:103]
	v_pk_add_f32 v[6:7], v[6:7], v[86:87]
	v_pk_add_f32 v[4:5], v[4:5], v[104:105]
	v_pk_add_f32 v[6:7], v[6:7], v[88:89]
	v_pk_add_f32 v[4:5], v[4:5], v[106:107]
	s_waitcnt lgkmcnt(0)
	v_mfma_f32_32x32x16_bf16 v[18:33], v[248:251], v[232:235], v[18:33]
	v_pk_add_f32 v[6:7], v[6:7], v[90:91]
	v_pk_add_f32 v[4:5], v[4:5], v[108:109]
	v_pk_add_f32 v[6:7], v[6:7], v[92:93]
	v_pk_add_f32 v[4:5], v[4:5], v[110:111]
	v_pk_add_f32 v[6:7], v[6:7], v[94:95]
	v_pk_add_f32 v[4:5], v[4:5], v[112:113]
	v_pk_add_f32 v[6:7], v[6:7], v[96:97]
	v_add_f32_e32 v6, v6, v7
	v_add_f32_e32 v4, v4, v5
	v_add_f32_e32 v4, v6, v4
	v_mov_b32_e32 v5, v4
	v_add_f32_e32 v225, v225, v4
	v_pk_add_f32 v[4:5], v[66:67], v[68:69]
	v_pk_add_f32 v[6:7], v[50:51], v[52:53]
	v_pk_add_f32 v[4:5], v[4:5], v[70:71]
	v_pk_add_f32 v[6:7], v[6:7], v[54:55]
	v_pk_add_f32 v[4:5], v[4:5], v[72:73]
	v_pk_add_f32 v[6:7], v[6:7], v[56:57]
	v_pk_add_f32 v[4:5], v[4:5], v[74:75]
	v_pk_add_f32 v[6:7], v[6:7], v[58:59]
	v_pk_add_f32 v[4:5], v[4:5], v[76:77]
	v_pk_add_f32 v[6:7], v[6:7], v[60:61]
	v_pk_add_f32 v[4:5], v[4:5], v[78:79]
	v_pk_add_f32 v[6:7], v[6:7], v[62:63]
	v_pk_add_f32 v[4:5], v[4:5], v[80:81]
	v_pk_add_f32 v[6:7], v[6:7], v[64:65]
	v_add_f32_e32 v6, v6, v7
	v_add_f32_e32 v4, v4, v5
	v_add_f32_e32 v4, v6, v4
	v_add_f32_e32 v225, v225, v4
	s_mov_b64 s[20:21], 0
	s_mov_b32 s30, 0x437f0000
	v_cmp_nge_f32_e32 vcc, s30, v5
	v_cmp_nge_f32_e64 s[98:99], s30, v4
	s_or_b64 s[98:99], vcc, s[98:99]
	s_cbranch_scc1 .Lm2_rare_full
	s_waitcnt vmcnt(0) lgkmcnt(0)
	s_barrier
	s_add_i32 s45, s45, 2
	s_branch .LBB0_1463

.Lm2_st:
	ds_read_b128 v[10:13], v8
	ds_read_b128 v[14:17], v8 offset:512
	ds_read_b128 v[174:177], v8 offset:2048
	ds_read_b128 v[178:181], v8 offset:2560
	ds_read_b128 v[182:185], v8 offset:4096
	ds_read_b128 v[186:189], v8 offset:4608
	ds_read_b128 v[228:231], v8 offset:6144
	ds_read_b128 v[232:235], v8 offset:6656
	v_mov_b32_e32 v83, v82
	v_mov_b64_e32 v[84:85], v[82:83]
	v_mov_b64_e32 v[86:87], v[82:83]
	v_mov_b64_e32 v[88:89], v[82:83]
	v_mov_b64_e32 v[90:91], v[82:83]
	v_mov_b64_e32 v[92:93], v[82:83]
	v_mov_b64_e32 v[94:95], v[82:83]
	v_mov_b64_e32 v[96:97], v[82:83]
	s_add_i32 s0, s21, 2
	s_ashr_i32 s1, s0, 31
	s_waitcnt lgkmcnt(7)
	v_mfma_f32_32x32x16_bf16 v[98:113], v[10:13], v[114:117], v[82:97]
	ds_read_b64_tr_b16 v[10:11], v3 offset:32768
	ds_read_b64_tr_b16 v[12:13], v3 offset:33280
	s_lshl_b64 s[0:1], s[0:1], 6
	s_add_u32 s0, s0, s84
	s_addc_u32 s1, s1, s85
	s_lshl_b64 s[0:1], s[0:1], 7
	s_add_u32 s28, s86, s0
	s_waitcnt lgkmcnt(8)
	v_mfma_f32_32x32x16_bf16 v[82:97], v[14:17], v[114:117], v[82:97]
	ds_read_b64_tr_b16 v[14:15], v3 offset:36864
	ds_read_b64_tr_b16 v[16:17], v3 offset:37376
	s_addc_u32 s29, s87, s1
	s_sub_i32 s31, s37, s30
	s_add_i32 s31, s31, 0x4000
	v_lshlrev_b32_e32 v5, 7, v138
	s_mov_b32 m0, s31
	s_waitcnt lgkmcnt(9)
	v_mfma_f32_32x32x16_bf16 v[98:113], v[174:177], v[118:121], v[98:113]
	ds_read_b64_tr_b16 v[174:175], v3 offset:33792
	ds_read_b64_tr_b16 v[176:177], v3 offset:34304
	s_movk_i32 s30, 0x80
	global_load_lds_dwordx4 v5, s[28:29]
	v_mad_u64_u32 v[226:227], vcc, v168, s30, v[134:135]
	s_waitcnt lgkmcnt(10)
	v_mfma_f32_32x32x16_bf16 v[82:97], v[178:181], v[118:121], v[82:97]
	ds_read_b64_tr_b16 v[178:179], v3 offset:37888
	ds_read_b64_tr_b16 v[180:181], v3 offset:38400
	s_add_i32 s31, s31, 0x8000
	v_lshl_add_u64 v[6:7], v[226:227], 0, s[0:1]
	s_mov_b32 m0, s31
	s_cmp_lt_i32 s45, s44
	global_load_lds_dwordx4 v[6:7], off
	s_waitcnt lgkmcnt(11)
	v_mfma_f32_32x32x16_bf16 v[98:113], v[182:185], v[122:125], v[98:113]
	ds_read_b64_tr_b16 v[182:183], v3 offset:34816
	ds_read_b64_tr_b16 v[184:185], v3 offset:35328
	s_cselect_b32 s98, 0x2000, 0
	s_add_u32 s28, s28, s98
	s_addc_u32 s29, s29, 0
	s_add_u32 s0, s0, s98
	s_addc_u32 s1, s1, 0
	s_waitcnt lgkmcnt(12)
	v_mfma_f32_32x32x16_bf16 v[82:97], v[186:189], v[122:125], v[82:97]
	ds_read_b64_tr_b16 v[186:187], v3 offset:38912
	ds_read_b64_tr_b16 v[188:189], v3 offset:39424
	s_sub_i32 s31, s31, 0x6000
	s_mov_b32 m0, s31
	v_lshl_add_u64 v[6:7], v[226:227], 0, s[0:1]
	global_load_lds_dwordx4 v5, s[28:29]
	s_waitcnt lgkmcnt(13)
	v_mfma_f32_32x32x16_bf16 v[98:113], v[228:231], v[126:129], v[98:113]
	ds_read_b64_tr_b16 v[228:229], v3 offset:35840
	ds_read_b64_tr_b16 v[230:231], v3 offset:36352
	s_add_i32 s31, s31, 0x8000
	s_mov_b32 m0, s31
	s_nop 0
	global_load_lds_dwordx4 v[6:7], off
	s_waitcnt lgkmcnt(14)
	v_mfma_f32_32x32x16_bf16 v[82:97], v[232:235], v[126:129], v[82:97]
	s_waitcnt lgkmcnt(13)
	ds_read_b64_tr_b16 v[232:233], v3 offset:39936
	ds_read_b64_tr_b16 v[234:235], v3 offset:40448
	s_nop 0
	s_nop 0
	s_nop 0
	s_nop 0
	s_nop 0
	s_nop 0
	s_nop 0
	s_nop 0
	s_nop 0
	v_exp_f32_e32 v98, v98
	v_exp_f32_e32 v99, v99
	v_exp_f32_e32 v100, v100
	v_exp_f32_e32 v101, v101
	v_exp_f32_e32 v102, v102
	v_exp_f32_e32 v103, v103
	v_exp_f32_e32 v104, v104
	v_exp_f32_e32 v105, v105
	v_cvt_pk_bf16_f32 v236, v98, v99
	v_cvt_pk_bf16_f32 v237, v100, v101
	v_cvt_pk_bf16_f32 v238, v102, v103
	v_cvt_pk_bf16_f32 v239, v104, v105
	v_exp_f32_e32 v106, v106
	v_exp_f32_e32 v107, v107
	s_waitcnt lgkmcnt(14)
	v_mfma_f32_32x32x16_bf16 v[34:49], v[236:239], v[10:13], v[34:49]
	v_exp_f32_e32 v108, v108
	v_exp_f32_e32 v109, v109
	v_exp_f32_e32 v110, v110
	s_waitcnt lgkmcnt(12)
	v_mfma_f32_32x32x16_bf16 v[18:33], v[236:239], v[14:17], v[18:33]
	v_exp_f32_e32 v111, v111
	v_exp_f32_e32 v112, v112
	v_exp_f32_e32 v113, v113
	v_cvt_pk_bf16_f32 v240, v106, v107
	v_cvt_pk_bf16_f32 v241, v108, v109
	v_cvt_pk_bf16_f32 v242, v110, v111
	v_cvt_pk_bf16_f32 v243, v112, v113
	v_exp_f32_e32 v82, v82
	v_exp_f32_e32 v83, v83
	s_waitcnt lgkmcnt(10)
	v_mfma_f32_32x32x16_bf16 v[34:49], v[240:243], v[174:177], v[34:49]
	v_exp_f32_e32 v84, v84
	v_exp_f32_e32 v85, v85
	v_exp_f32_e32 v86, v86
	s_waitcnt lgkmcnt(8)
	v_mfma_f32_32x32x16_bf16 v[18:33], v[240:243], v[178:181], v[18:33]
	v_exp_f32_e32 v87, v87
	v_exp_f32_e32 v88, v88
	v_exp_f32_e32 v89, v89
	v_cvt_pk_bf16_f32 v244, v82, v83
	v_cvt_pk_bf16_f32 v245, v84, v85
	v_cvt_pk_bf16_f32 v246, v86, v87
	v_cvt_pk_bf16_f32 v247, v88, v89
	v_exp_f32_e32 v90, v90
	v_exp_f32_e32 v91, v91
	s_waitcnt lgkmcnt(6)
	v_mfma_f32_32x32x16_bf16 v[34:49], v[244:247], v[182:185], v[34:49]
	v_exp_f32_e32 v92, v92
	v_exp_f32_e32 v93, v93
	v_exp_f32_e32 v94, v94
	s_waitcnt lgkmcnt(4)
	v_mfma_f32_32x32x16_bf16 v[18:33], v[244:247], v[186:189], v[18:33]
	v_exp_f32_e32 v95, v95
	v_exp_f32_e32 v96, v96
	v_exp_f32_e32 v97, v97
	v_cvt_pk_bf16_f32 v248, v90, v91
	v_cvt_pk_bf16_f32 v249, v92, v93
	v_cvt_pk_bf16_f32 v250, v94, v95
	v_cvt_pk_bf16_f32 v251, v96, v97
	v_pk_add_f32 v[4:5], v[98:99], v[100:101]
	v_pk_add_f32 v[6:7], v[82:83], v[84:85]
	s_waitcnt lgkmcnt(2)
	v_mfma_f32_32x32x16_bf16 v[34:49], v[248:251], v[228:231], v[34:49]
	v_pk_add_f32 v[4:5], v[4:5], v[102:103]
	v_pk_add_f32 v[6:7], v[6:7], v[86:87]
	v_pk_add_f32 v[4:5], v[4:5], v[104:105]
	v_pk_add_f32 v[6:7], v[6:7], v[88:89]
	v_pk_add_f32 v[4:5], v[4:5], v[106:107]
	s_waitcnt lgkmcnt(0)
	v_mfma_f32_32x32x16_bf16 v[18:33], v[248:251], v[232:235], v[18:33]
	v_pk_add_f32 v[6:7], v[6:7], v[90:91]
	v_pk_add_f32 v[4:5], v[4:5], v[108:109]
	v_pk_add_f32 v[6:7], v[6:7], v[92:93]
	v_pk_add_f32 v[4:5], v[4:5], v[110:111]
	v_pk_add_f32 v[6:7], v[6:7], v[94:95]
	v_pk_add_f32 v[4:5], v[4:5], v[112:113]
	v_pk_add_f32 v[6:7], v[6:7], v[96:97]
	v_add_f32_e32 v6, v6, v7
	v_add_f32_e32 v4, v4, v5
	v_add_f32_e32 v4, v6, v4
	v_mov_b32_e32 v5, v4
	v_add_f32_e32 v225, v225, v4
	s_mov_b64 s[20:21], 0
	s_mov_b32 s30, 0x437f0000
	v_cmp_nge_f32_e32 vcc, s30, v5
	s_cmp_lg_u64 vcc, 0
	s_cbranch_scc1 .Lm2_rare_st
	s_waitcnt vmcnt(0) lgkmcnt(0)
	s_barrier
	s_add_i32 s45, s45, 2
	s_branch .LBB0_1463

.LBB0_1476:
	s_cmp_lt_u32 s63, 2
	s_cbranch_scc1 .Lhb_orig
	s_or_b64 s[98:99], s[0:1], s[96:97]
	s_cbranch_scc1 .Lhb_orig
	v_cmp_eq_f32_e64 s[18:19], s73, v222
	s_cmp_lg_u64 s[18:19], 0
	s_cbranch_scc1 .Lhb_full
	s_lshl_b32 s30, s20, 13
	v_add_u32_e32 v8, s30, v169
	v_add_u32_e32 v3, s30, v193
	ds_read_b128 v[10:13], v8
	ds_read_b128 v[14:17], v8 offset:512
	ds_read_b128 v[174:177], v8 offset:2048
	ds_read_b128 v[178:181], v8 offset:2560
	ds_read_b128 v[182:185], v8 offset:4096
	ds_read_b128 v[186:189], v8 offset:4608
	ds_read_b128 v[228:231], v8 offset:6144
	ds_read_b128 v[232:235], v8 offset:6656
	v_cmp_eq_f32_e64 s[18:19], s73, v222
	s_mov_b64 s[20:21], 0
	s_nop 0
	v_cndmask_b32_e64 v7, -v222, v204, s[18:19]
	v_add_f32_e32 v82, v7, v9
	v_add_f32_e32 v50, v7, v4
	v_mov_b32_e32 v83, v82
	v_mov_b64_e32 v[84:85], v[82:83]
	v_mov_b64_e32 v[86:87], v[82:83]
	v_mov_b64_e32 v[88:89], v[82:83]
	v_mov_b64_e32 v[90:91], v[82:83]
	v_mov_b64_e32 v[92:93], v[82:83]
	v_mov_b64_e32 v[94:95], v[82:83]
	v_mov_b64_e32 v[96:97], v[82:83]
	v_mov_b32_e32 v51, v50
	v_mov_b64_e32 v[52:53], v[50:51]
	s_waitcnt lgkmcnt(7)
	v_mfma_f32_32x32x16_bf16 v[98:113], v[10:13], v[114:117], v[82:97]
	ds_read_b128 v[10:13], v8 offset:8192
	v_mov_b64_e32 v[54:55], v[50:51]
	v_mov_b64_e32 v[56:57], v[50:51]
	v_mov_b64_e32 v[58:59], v[50:51]
	v_mov_b64_e32 v[60:61], v[50:51]
	v_mov_b64_e32 v[62:63], v[50:51]
	s_waitcnt lgkmcnt(7)
	v_mfma_f32_32x32x16_bf16 v[82:97], v[14:17], v[114:117], v[82:97]
	ds_read_b128 v[14:17], v8 offset:8704
	v_mov_b64_e32 v[64:65], v[50:51]
	s_waitcnt lgkmcnt(7)
	v_mfma_f32_32x32x16_bf16 v[98:113], v[174:177], v[118:121], v[98:113]
	ds_read_b128 v[174:177], v8 offset:10240
	s_waitcnt lgkmcnt(7)
	v_mfma_f32_32x32x16_bf16 v[82:97], v[178:181], v[118:121], v[82:97]
	ds_read_b128 v[178:181], v8 offset:10752
	s_waitcnt lgkmcnt(7)
	v_mfma_f32_32x32x16_bf16 v[98:113], v[182:185], v[122:125], v[98:113]
	ds_read_b128 v[182:185], v8 offset:12288
	s_waitcnt lgkmcnt(7)
	v_mfma_f32_32x32x16_bf16 v[82:97], v[186:189], v[122:125], v[82:97]
	ds_read_b128 v[186:189], v8 offset:12800
	s_waitcnt lgkmcnt(7)
	v_mfma_f32_32x32x16_bf16 v[98:113], v[228:231], v[126:129], v[98:113]
	ds_read_b128 v[228:231], v8 offset:14336
	s_waitcnt lgkmcnt(7)
	v_mfma_f32_32x32x16_bf16 v[82:97], v[232:235], v[126:129], v[82:97]
	ds_read_b128 v[232:235], v8 offset:14848
	s_waitcnt lgkmcnt(7)
	v_mfma_f32_32x32x16_bf16 v[66:81], v[10:13], v[114:117], v[50:65]
	ds_read_b64_tr_b16 v[10:11], v3 offset:32768
	ds_read_b64_tr_b16 v[12:13], v3 offset:33280
	s_waitcnt lgkmcnt(8)
	v_mfma_f32_32x32x16_bf16 v[50:65], v[14:17], v[114:117], v[50:65]
	ds_read_b64_tr_b16 v[14:15], v3 offset:36864
	ds_read_b64_tr_b16 v[16:17], v3 offset:37376
	s_waitcnt lgkmcnt(9)
	v_mfma_f32_32x32x16_bf16 v[66:81], v[174:177], v[118:121], v[66:81]
	ds_read_b64_tr_b16 v[174:175], v3 offset:33792
	ds_read_b64_tr_b16 v[176:177], v3 offset:34304
	v_exp_f32_e32 v98, v98
	v_exp_f32_e32 v99, v99
	v_exp_f32_e32 v100, v100
	s_waitcnt lgkmcnt(10)
	v_mfma_f32_32x32x16_bf16 v[50:65], v[178:181], v[118:121], v[50:65]
	ds_read_b64_tr_b16 v[178:179], v3 offset:37888
	ds_read_b64_tr_b16 v[180:181], v3 offset:38400
	v_exp_f32_e32 v101, v101
	v_exp_f32_e32 v102, v102
	v_exp_f32_e32 v103, v103
	s_waitcnt lgkmcnt(11)
	v_mfma_f32_32x32x16_bf16 v[66:81], v[182:185], v[122:125], v[66:81]
	ds_read_b64_tr_b16 v[182:183], v3 offset:34816
	ds_read_b64_tr_b16 v[184:185], v3 offset:35328
	v_exp_f32_e32 v104, v104
	v_exp_f32_e32 v105, v105
	v_cvt_pk_bf16_f32 v236, v98, v99
	s_waitcnt lgkmcnt(12)
	v_mfma_f32_32x32x16_bf16 v[50:65], v[186:189], v[122:125], v[50:65]
	ds_read_b64_tr_b16 v[186:187], v3 offset:38912
	ds_read_b64_tr_b16 v[188:189], v3 offset:39424
	v_cvt_pk_bf16_f32 v237, v100, v101
	v_cvt_pk_bf16_f32 v238, v102, v103
	v_cvt_pk_bf16_f32 v239, v104, v105
	v_exp_f32_e32 v106, v106
	s_waitcnt lgkmcnt(13)
	v_mfma_f32_32x32x16_bf16 v[66:81], v[228:231], v[126:129], v[66:81]
	ds_read_b64_tr_b16 v[228:229], v3 offset:35840
	ds_read_b64_tr_b16 v[230:231], v3 offset:36352
	v_exp_f32_e32 v107, v107
	v_exp_f32_e32 v108, v108
	v_exp_f32_e32 v109, v109
	s_waitcnt lgkmcnt(14)
	v_mfma_f32_32x32x16_bf16 v[50:65], v[232:235], v[126:129], v[50:65]
	s_waitcnt lgkmcnt(13)
	ds_read_b64_tr_b16 v[232:233], v3 offset:39936
	ds_read_b64_tr_b16 v[234:235], v3 offset:40448
	v_exp_f32_e32 v110, v110
	v_exp_f32_e32 v111, v111
	v_exp_f32_e32 v112, v112
	s_waitcnt lgkmcnt(14)
	v_mfma_f32_32x32x16_bf16 v[34:49], v[236:239], v[10:13], v[34:49]
	s_waitcnt lgkmcnt(13)
	ds_read_b64_tr_b16 v[10:11], v3 offset:40960
	ds_read_b64_tr_b16 v[12:13], v3 offset:41472
	v_exp_f32_e32 v113, v113
	v_cvt_pk_bf16_f32 v240, v106, v107
	v_cvt_pk_bf16_f32 v241, v108, v109
	v_cvt_pk_bf16_f32 v242, v110, v111
	s_waitcnt lgkmcnt(14)
	v_mfma_f32_32x32x16_bf16 v[18:33], v[236:239], v[14:17], v[18:33]
	s_waitcnt lgkmcnt(13)
	ds_read_b64_tr_b16 v[14:15], v3 offset:45056
	ds_read_b64_tr_b16 v[16:17], v3 offset:45568
	v_cvt_pk_bf16_f32 v243, v112, v113
	v_exp_f32_e32 v82, v82
	v_exp_f32_e32 v83, v83
	s_waitcnt lgkmcnt(14)
	v_mfma_f32_32x32x16_bf16 v[34:49], v[240:243], v[174:177], v[34:49]
	s_waitcnt lgkmcnt(13)
	ds_read_b64_tr_b16 v[174:175], v3 offset:41984
	ds_read_b64_tr_b16 v[176:177], v3 offset:42496
	v_exp_f32_e32 v84, v84
	v_exp_f32_e32 v85, v85
	v_exp_f32_e32 v86, v86
	s_waitcnt lgkmcnt(14)
	v_mfma_f32_32x32x16_bf16 v[18:33], v[240:243], v[178:181], v[18:33]
	s_waitcnt lgkmcnt(13)
	ds_read_b64_tr_b16 v[178:179], v3 offset:46080
	ds_read_b64_tr_b16 v[180:181], v3 offset:46592
	v_exp_f32_e32 v87, v87
	v_exp_f32_e32 v88, v88
	v_exp_f32_e32 v89, v89
	v_cvt_pk_bf16_f32 v244, v82, v83
	v_cvt_pk_bf16_f32 v245, v84, v85
	v_cvt_pk_bf16_f32 v246, v86, v87
	v_cvt_pk_bf16_f32 v247, v88, v89
	v_exp_f32_e32 v90, v90
	v_exp_f32_e32 v91, v91
	s_waitcnt lgkmcnt(14)
	v_mfma_f32_32x32x16_bf16 v[34:49], v[244:247], v[182:185], v[34:49]
	s_waitcnt lgkmcnt(13)
	ds_read_b64_tr_b16 v[182:183], v3 offset:43008
	ds_read_b64_tr_b16 v[184:185], v3 offset:43520
	v_exp_f32_e32 v92, v92
	v_exp_f32_e32 v93, v93
	v_exp_f32_e32 v94, v94
	s_waitcnt lgkmcnt(14)
	v_mfma_f32_32x32x16_bf16 v[18:33], v[244:247], v[186:189], v[18:33]
	s_waitcnt lgkmcnt(13)
	ds_read_b64_tr_b16 v[186:187], v3 offset:47104
	ds_read_b64_tr_b16 v[188:189], v3 offset:47616
	v_exp_f32_e32 v95, v95
	v_exp_f32_e32 v96, v96
	v_exp_f32_e32 v97, v97
	v_cvt_pk_bf16_f32 v248, v90, v91
	v_cvt_pk_bf16_f32 v249, v92, v93
	v_cvt_pk_bf16_f32 v250, v94, v95
	v_cvt_pk_bf16_f32 v251, v96, v97
	v_exp_f32_e32 v66, v66
	v_exp_f32_e32 v67, v67
	s_waitcnt lgkmcnt(14)
	v_mfma_f32_32x32x16_bf16 v[34:49], v[248:251], v[228:231], v[34:49]
	s_waitcnt lgkmcnt(13)
	ds_read_b64_tr_b16 v[228:229], v3 offset:44032
	ds_read_b64_tr_b16 v[230:231], v3 offset:44544
	v_exp_f32_e32 v68, v68
	v_exp_f32_e32 v69, v69
	v_exp_f32_e32 v70, v70
	s_waitcnt lgkmcnt(14)
	v_mfma_f32_32x32x16_bf16 v[18:33], v[248:251], v[232:235], v[18:33]
	s_waitcnt lgkmcnt(13)
	ds_read_b64_tr_b16 v[232:233], v3 offset:48128
	ds_read_b64_tr_b16 v[234:235], v3 offset:48640
	v_exp_f32_e32 v71, v71
	v_exp_f32_e32 v72, v72
	v_exp_f32_e32 v73, v73
	v_cvt_pk_bf16_f32 v236, v66, v67
	v_cvt_pk_bf16_f32 v237, v68, v69
	v_cvt_pk_bf16_f32 v238, v70, v71
	v_cvt_pk_bf16_f32 v239, v72, v73
	v_exp_f32_e32 v74, v74
	v_exp_f32_e32 v75, v75
	s_waitcnt lgkmcnt(14)
	v_mfma_f32_32x32x16_bf16 v[34:49], v[236:239], v[10:13], v[34:49]
	v_exp_f32_e32 v76, v76
	v_exp_f32_e32 v77, v77
	v_exp_f32_e32 v78, v78
	s_waitcnt lgkmcnt(12)
	v_mfma_f32_32x32x16_bf16 v[18:33], v[236:239], v[14:17], v[18:33]
	v_exp_f32_e32 v79, v79
	v_exp_f32_e32 v80, v80
	v_exp_f32_e32 v81, v81
	v_cvt_pk_bf16_f32 v240, v74, v75
	v_cvt_pk_bf16_f32 v241, v76, v77
	v_cvt_pk_bf16_f32 v242, v78, v79
	v_cvt_pk_bf16_f32 v243, v80, v81
	v_exp_f32_e32 v50, v50
	v_exp_f32_e32 v51, v51
	s_waitcnt lgkmcnt(10)
	v_mfma_f32_32x32x16_bf16 v[34:49], v[240:243], v[174:177], v[34:49]
	v_exp_f32_e32 v52, v52
	v_exp_f32_e32 v53, v53
	v_exp_f32_e32 v54, v54
	s_waitcnt lgkmcnt(8)
	v_mfma_f32_32x32x16_bf16 v[18:33], v[240:243], v[178:181], v[18:33]
	v_exp_f32_e32 v55, v55
	v_exp_f32_e32 v56, v56
	v_exp_f32_e32 v57, v57
	v_cvt_pk_bf16_f32 v244, v50, v51
	v_cvt_pk_bf16_f32 v245, v52, v53
	v_cvt_pk_bf16_f32 v246, v54, v55
	v_cvt_pk_bf16_f32 v247, v56, v57
	v_exp_f32_e32 v58, v58
	v_exp_f32_e32 v59, v59
	s_waitcnt lgkmcnt(6)
	v_mfma_f32_32x32x16_bf16 v[34:49], v[244:247], v[182:185], v[34:49]
	v_exp_f32_e32 v60, v60
	v_exp_f32_e32 v61, v61
	v_exp_f32_e32 v62, v62
	s_waitcnt lgkmcnt(4)
	v_mfma_f32_32x32x16_bf16 v[18:33], v[244:247], v[186:189], v[18:33]
	v_exp_f32_e32 v63, v63
	v_exp_f32_e32 v64, v64
	v_exp_f32_e32 v65, v65
	v_cvt_pk_bf16_f32 v248, v58, v59
	v_cvt_pk_bf16_f32 v249, v60, v61
	v_cvt_pk_bf16_f32 v250, v62, v63
	v_cvt_pk_bf16_f32 v251, v64, v65
	v_pk_add_f32 v[4:5], v[98:99], v[100:101]
	v_pk_add_f32 v[6:7], v[82:83], v[84:85]
	s_waitcnt lgkmcnt(2)
	v_mfma_f32_32x32x16_bf16 v[34:49], v[248:251], v[228:231], v[34:49]
	v_pk_add_f32 v[4:5], v[4:5], v[102:103]
	v_pk_add_f32 v[6:7], v[6:7], v[86:87]
	v_pk_add_f32 v[4:5], v[4:5], v[104:105]
	v_pk_add_f32 v[6:7], v[6:7], v[88:89]
	v_pk_add_f32 v[4:5], v[4:5], v[106:107]
	s_waitcnt lgkmcnt(0)
	v_mfma_f32_32x32x16_bf16 v[18:33], v[248:251], v[232:235], v[18:33]
	v_pk_add_f32 v[6:7], v[6:7], v[90:91]
	v_pk_add_f32 v[4:5], v[4:5], v[108:109]
	v_pk_add_f32 v[6:7], v[6:7], v[92:93]
	v_pk_add_f32 v[4:5], v[4:5], v[110:111]
	v_pk_add_f32 v[6:7], v[6:7], v[94:95]
	v_pk_add_f32 v[4:5], v[4:5], v[112:113]
	v_pk_add_f32 v[6:7], v[6:7], v[96:97]
	v_add_f32_e32 v6, v6, v7
	v_add_f32_e32 v4, v4, v5
	v_add_f32_e32 v4, v6, v4
	v_mov_b32_e32 v5, v4
	v_add_f32_e32 v225, v225, v4
	v_pk_add_f32 v[4:5], v[66:67], v[68:69]
	v_pk_add_f32 v[6:7], v[50:51], v[52:53]
	v_pk_add_f32 v[4:5], v[4:5], v[70:71]
	v_pk_add_f32 v[6:7], v[6:7], v[54:55]
	v_pk_add_f32 v[4:5], v[4:5], v[72:73]
	v_pk_add_f32 v[6:7], v[6:7], v[56:57]
	v_pk_add_f32 v[4:5], v[4:5], v[74:75]
	v_pk_add_f32 v[6:7], v[6:7], v[58:59]
	v_pk_add_f32 v[4:5], v[4:5], v[76:77]
	v_pk_add_f32 v[6:7], v[6:7], v[60:61]
	v_pk_add_f32 v[4:5], v[4:5], v[78:79]
	v_pk_add_f32 v[6:7], v[6:7], v[62:63]
	v_pk_add_f32 v[4:5], v[4:5], v[80:81]
	v_pk_add_f32 v[6:7], v[6:7], v[64:65]
	v_add_f32_e32 v6, v6, v7
	v_add_f32_e32 v4, v4, v5
	v_add_f32_e32 v4, v6, v4
	v_add_f32_e32 v225, v225, v4
	s_mov_b32 s30, 0x437f0000
	v_cmp_nge_f32_e32 vcc, s30, v5
	v_cmp_nge_f32_e64 s[98:99], s30, v4
	s_mov_b64 s[28:29], 0
	s_mov_b64 s[0:1], 0
	s_or_b64 s[98:99], vcc, s[98:99]
	s_cbranch_scc0 .LBB0_1492
	v_max3_f32 v5, v98, v99, v100
	v_max3_f32 v6, v106, v107, v108
	v_max3_f32 v9, v82, v83, v84
	v_max3_f32 v227, v90, v91, v92
	v_max3_f32 v5, v5, v101, v102
	v_max3_f32 v6, v6, v109, v110
	v_max3_f32 v9, v9, v85, v86
	v_max3_f32 v227, v227, v93, v94
	v_max3_f32 v5, v5, v103, v104
	v_max3_f32 v6, v6, v111, v112
	v_max3_f32 v9, v9, v87, v88
	v_max3_f32 v227, v227, v95, v96
	v_max3_f32 v5, v5, v105, v113
	v_max3_f32 v9, v9, v89, v97
	v_max3_f32 v5, v5, v6, v9
	v_max_f32_e32 v5, v5, v227
	v_mov_b32_e32 v6, v5
	s_nop 1
	v_permlane32_swap_b32_e32 v5, v6
	v_max_f32_e32 v5, v5, v6
	v_log_f32_e32 v5, v5
	s_nop 0
	v_cmp_lt_f32_e32 vcc, s74, v5
	s_and_b64 s[28:29], s[18:19], vcc
	v_cmp_lt_f32_e32 vcc, s75, v5
	s_or_b64 s[28:29], vcc, s[28:29]
	s_nop 0
	v_cndmask_b32_e64 v252, 0, v5, s[28:29]
	s_cselect_b64 s[28:29], -1, 0
	v_max3_f32 v5, v66, v67, v68
	v_max3_f32 v6, v74, v75, v76
	v_max3_f32 v9, v50, v51, v52
	v_max3_f32 v227, v58, v59, v60
	v_max3_f32 v5, v5, v69, v70
	v_max3_f32 v6, v6, v77, v78
	v_max3_f32 v9, v9, v53, v54
	v_max3_f32 v227, v227, v61, v62
	v_max3_f32 v5, v5, v71, v72
	v_max3_f32 v6, v6, v79, v80
	v_max3_f32 v9, v9, v55, v56
	v_max3_f32 v227, v227, v63, v64
	v_max3_f32 v5, v5, v73, v81
	v_max3_f32 v9, v9, v57, v65
	v_max3_f32 v5, v5, v6, v9
	v_max_f32_e32 v5, v5, v227
	v_mov_b32_e32 v6, v5
	s_nop 1
	v_permlane32_swap_b32_e32 v5, v6
	v_max_f32_e32 v5, v5, v6
	v_log_f32_e32 v5, v5
	s_nop 0
	v_cmp_lt_f32_e32 vcc, s74, v5
	s_and_b64 s[0:1], s[18:19], vcc
	v_cmp_lt_f32_e32 vcc, s75, v5
	s_or_b64 s[0:1], vcc, s[0:1]
	s_nop 0
	v_cndmask_b32_e64 v101, 0, v5, s[0:1]
	s_cselect_b64 s[0:1], -1, 0
	v_mov_b32_e32 v228, v252
	s_branch .LBB0_1492
